# hand-written ret_inter (tr-reads, direct Q fragments, 3-deep prefetch, XCD-local unit map) + XCD-local scan unit map
# speedup vs baseline: 1.0670x; 1.0087x over previous
; #define TIDX tid_fn()
; __device__ __forceinline__ void ph_ret_inter(const Params& P, char* smem) {
;     ...
;   const int tid = TIDX, wave = tid >> 6, lane = tid & 63;
;   for (int u = blockIdx.x; u < NU; u += gridDim.x) {
;     const int dvs = u % 8, dir = (u / 8) % 2, h = (u / 16) % RET_HEADS, b = u / (16 * RET_HEADS);
;     const float lg = ret_lg(h, dir);
;     const float gC = expf(lg * (float)RET_C);
;     __syncthreads();
;     if (tid < 128) {
;       dec[tid] = dir == 0 ? expf(lg * (float)(tid + 1)) : expf(lg * (float)(RET_C - tid));
;       wk[tid] = dir == 0 ? expf(lg * (float)(RET_C - 1 - tid)) : expf(lg * (float)tid);
;     }
;     for (int i = tid; i < 2 * 16 * LDR; i += NTHR) St[i] = (h16)0.f;
;     f32x4 accS = (f32x4){0.f, 0.f, 0.f, 0.f};
;     auto chunk_of = [&](int o) -> int {
;       if (o < RET_CCH) return RET_LCH + (dir == 0 ? o : RET_CCH - 1 - o);
;       return dir == 0 ? (o - RET_CCH) : (RET_LCH - 1 - (o - RET_CCH));
;     };
;     h16x8 rq[4], rk[4], rv;
;     ...
;     RI_FETCH(0);
.LBB0_1228:
	s_or_b64 exec, exec, s[6:7]
	s_mov_b64 s[4:5], s[96:97]
	v_mov_b32_e32 v2, v0
	s_cmpk_gt_i32 s2, 0xff
	s_movk_i32 s12, 0xff
	s_waitcnt lgkmcnt(0)
	s_barrier
	s_cmpk_gt_u32 s2, 0xff
	s_cbranch_scc1 .LBB0_1262
	s_load_dwordx4 s[16:19], s[96:97], 0x170
	v_readfirstlane_b32 s0, v0
	s_lshr_b32 s0, s0, 6
	v_and_b32_e32 v232, 63, v0
	v_and_b32_e32 v233, 15, v232
	v_lshrrev_b32_e32 v234, 4, v232
	v_lshrrev_b32_e32 v235, 2, v233
	v_and_b32_e32 v236, 3, v233
	v_lshrrev_b32_e32 v237, 4, v0
	v_and_b32_e32 v238, 15, v0
	v_mul_u32_u24_e32 v10, 288, v237
	v_lshl_add_u32 v10, v238, 4, v10
	v_lshrrev_b32_e32 v208, 1, v0
	v_and_b32_e32 v209, 1, v0
	v_mul_u32_u24_e32 v11, 48, v208
	v_lshl_add_u32 v11, v209, 4, v11
	v_add_u32_e32 v11, 0x12000, v11
	v_mul_u32_u24_e32 v13, 272, v233
	v_lshl_add_u32 v13, v234, 4, v13
	v_add_u32_e32 v13, 0x15000, v13
	v_lshl_add_u32 v211, v234, 3, v235
	v_mul_u32_u24_e32 v14, 288, v211
	v_lshl_add_u32 v14, v236, 3, v14
	s_lshl_b32 s1, s0, 5
	v_add_u32_e32 v14, s1, v14
	v_add_u32_e32 v12, 0x9000, v14
	v_mul_u32_u24_e32 v15, 48, v211
	v_lshl_add_u32 v15, v236, 3, v15
	v_add_u32_e32 v15, 0x12000, v15
	v_mul_u32_u24_e32 v16, 272, v233
	v_lshl_add_u32 v16, v234, 3, v16
	v_add_u32_e32 v16, s1, v16
	v_add_u32_e32 v16, 0x15000, v16
	s_waitcnt lgkmcnt(0)
	s_add_u32 s24, s18, 0x160cc000
	s_addc_u32 s25, s19, 0
	s_mov_b32 s6, s2
.Lri_unit:
	s_and_b32 s1, s6, 7
	s_lshr_b32 s14, s6, 3
	s_and_b32 s7, s14, 7
	s_lshr_b32 s14, s14, 3
	s_lshl_b32 s1, s1, 2
	s_add_u32 s1, s1, s14
	s_and_b32 s8, s1, 1
	s_bfe_u32 s9, s1, 0x30001
	s_lshr_b32 s10, s1, 4
	s_sub_u32 s1, 7, s9
	s_cmp_lg_u32 s8, 0
	s_cselect_b32 s1, s1, s9
	s_mov_b32 s12, 0xbd3b9ca6
	s_cmp_eq_u32 s1, 1
	s_cselect_b32 s12, 0xbcba1f74, s12
	s_cmp_eq_u32 s1, 2
	s_cselect_b32 s12, 0xbc3963dd, s12
	s_cmp_eq_u32 s1, 3
	s_cselect_b32 s12, 0xbbb906ce, s12
	s_cmp_eq_u32 s1, 4
	s_cselect_b32 s12, 0xbb38d875, s12
	s_cmp_eq_u32 s1, 5
	s_cselect_b32 s12, 0xbab8c154, s12
	s_cmp_eq_u32 s1, 6
	s_cselect_b32 s12, 0xba38b5c7, s12
	s_cmp_eq_u32 s1, 7
	s_cselect_b32 s12, 0xb9b8b001, s12
	v_mov_b32_e32 v208, s12
	v_mul_f32_e32 v208, 0x43000000, v208
	v_exp_f32_e32 v208, v208
	s_nop 0
	v_readfirstlane_b32 s13, v208
	s_lshl_b32 s1, s0, 4
	v_lshl_add_u32 v209, v234, 2, s1
	s_cmp_lg_u32 s8, 0
	s_cselect_b64 vcc, -1, 0
	v_add_u32_e32 v210, 0, v209
	v_add_u32_e32 v211, 1, v210
	v_sub_u32_e32 v212, 0x80, v210
	v_cndmask_b32_e32 v211, v211, v212, vcc
	v_cvt_f32_u32_e32 v211, v211
	v_mul_f32_e32 v211, s12, v211
	v_exp_f32_e32 v128, v211
	v_add_u32_e32 v210, 1, v209
	v_add_u32_e32 v211, 1, v210
	v_sub_u32_e32 v212, 0x80, v210
	v_cndmask_b32_e32 v211, v211, v212, vcc
	v_cvt_f32_u32_e32 v211, v211
	v_mul_f32_e32 v211, s12, v211
	v_exp_f32_e32 v129, v211
	v_add_u32_e32 v210, 2, v209
	v_add_u32_e32 v211, 1, v210
	v_sub_u32_e32 v212, 0x80, v210
	v_cndmask_b32_e32 v211, v211, v212, vcc
	v_cvt_f32_u32_e32 v211, v211
	v_mul_f32_e32 v211, s12, v211
	v_exp_f32_e32 v130, v211
	v_add_u32_e32 v210, 3, v209
	v_add_u32_e32 v211, 1, v210
	v_sub_u32_e32 v212, 0x80, v210
	v_cndmask_b32_e32 v211, v211, v212, vcc
	v_cvt_f32_u32_e32 v211, v211
	v_mul_f32_e32 v211, s12, v211
	v_exp_f32_e32 v131, v211
	v_lshrrev_b32_e32 v210, 1, v0
	v_sub_u32_e32 v211, 0x7f, v210
	v_cndmask_b32_e32 v211, v211, v210, vcc
	v_cvt_f32_u32_e32 v211, v211
	v_mul_f32_e32 v211, s12, v211
	v_exp_f32_e32 v19, v211
	s_lshl_b32 s1, s9, 8
	s_add_u32 s1, s1, 0x1800
	v_mul_u32_u24_e32 v213, 0x3800, v237
	v_lshl_add_u32 v213, v238, 4, v213
	s_add_u32 s14, s1, 0x800
	v_add_u32_e32 v4, s14, v213
	v_add_u32_e32 v5, 0x70000, v4
	v_add_u32_e32 v6, 0xe0000, v4
	v_add_u32_e32 v7, 0x150000, v4
	v_lshrrev_b32_e32 v210, 1, v0
	v_and_b32_e32 v211, 1, v0
	v_mul_u32_u24_e32 v8, 0x3800, v210
	v_lshl_add_u32 v8, v211, 4, v8
	s_lshl_b32 s14, s7, 5
	s_add_u32 s14, s14, s1
	s_add_u32 s14, s14, 0x1000
	v_add_u32_e32 v8, s14, v8
	s_lshl_b32 s14, s0, 4
	v_add_u32_e32 v210, s14, v233
	v_mul_u32_u24_e32 v9, 0x3800, v210
	v_lshl_add_u32 v9, v234, 4, v9
	v_add_u32_e32 v9, s1, v9
	s_lshl_b32 s14, s9, 7
	s_lshl_b32 s15, s7, 4
	s_add_u32 s14, s14, s15
	v_lshlrev_b32_e32 v17, 10, v209
	v_add_u32_e32 v17, s14, v17
	v_add_lshl_u32 v17, v17, v233, 1
	v_add_u32_e32 v18, 0x1000, v17
	v_mov_b32_e32 v132, 0
	v_mov_b32_e32 v133, 0
	v_mov_b32_e32 v134, 0
	v_mov_b32_e32 v135, 0
	v_mov_b32_e32 v216, 0
	v_mov_b32_e32 v217, 0
	v_mov_b32_e32 v218, 0
	v_mov_b32_e32 v219, 0
	v_lshlrev_b32_e32 v214, 4, v0
	v_add_u32_e32 v214, 0x15000, v214
	v_cmp_gt_u32_e32 vcc, 0x110, v0
	s_and_saveexec_b64 s[26:27], vcc
	ds_write_b128 v214, v[216:219]
	s_mov_b64 exec, s[26:27]
	s_mov_b32 s11, 0
	s_mov_b32 s26, 0
	s_cmp_lt_u32 s26, 2
	s_cbranch_scc0 .Lri_lat_0
	s_sub_u32 s1, 1, s26
	s_cmp_lg_u32 s8, 0
	s_cselect_b32 s1, s1, s26
	s_lshl_b32 s1, s1, 7
	s_lshl_b32 s14, s10, 8
	s_add_u32 s1, s1, s14
	s_add_u32 s1, s1, 0x8000
	s_branch .Lri_rowdone_0
.Lri_lat_0:
	s_sub_u32 s1, s26, 2
	s_sub_u32 s14, 0x81, s26
	s_cmp_lg_u32 s8, 0
	s_cselect_b32 s1, s14, s1
	s_lshl_b32 s1, s1, 7
	s_lshl_b32 s14, s10, 14
	s_add_u32 s1, s1, s14
.Lri_rowdone_0:
	s_mul_i32 s14, s1, 0x3800
	s_add_u32 s20, s24, s14
	s_addc_u32 s21, s25, 0
	global_load_dwordx4 v[36:39], v4, s[20:21]
	global_load_dwordx4 v[40:43], v5, s[20:21]
	global_load_dwordx4 v[44:47], v6, s[20:21]
	global_load_dwordx4 v[48:51], v7, s[20:21]
	global_load_dwordx4 v[52:55], v8, s[20:21]
	global_load_dwordx4 v[20:23], v9, s[20:21]
	global_load_dwordx4 v[24:27], v9, s[20:21] offset:64
	global_load_dwordx4 v[28:31], v9, s[20:21] offset:128
	global_load_dwordx4 v[32:35], v9, s[20:21] offset:192
	s_mov_b32 s26, 1
	s_cmp_lt_u32 s26, 2
	s_cbranch_scc0 .Lri_lat_1
	s_sub_u32 s1, 1, s26
	s_cmp_lg_u32 s8, 0
	s_cselect_b32 s1, s1, s26
	s_lshl_b32 s1, s1, 7
	s_lshl_b32 s14, s10, 8
	s_add_u32 s1, s1, s14
	s_add_u32 s1, s1, 0x8000
	s_branch .Lri_rowdone_1

; __device__ __forceinline__ void ph_ret_inter(const Params& P, char* smem) {
;     ...
;     auto chunk_of = [&](int o) -> int {
;       if (o < RET_CCH) return RET_LCH + (dir == 0 ? o : RET_CCH - 1 - o);
;       return dir == 0 ? (o - RET_CCH) : (RET_LCH - 1 - (o - RET_CCH));
;     };
;     h16x8 rq[4], rk[4], rv;
;     ...
;     RI_FETCH(0);
.Lri_rowdone_1:
	s_mul_i32 s14, s1, 0x3800
	s_add_u32 s20, s24, s14
	s_addc_u32 s21, s25, 0
	global_load_dwordx4 v[72:75], v4, s[20:21]
	global_load_dwordx4 v[76:79], v5, s[20:21]
	global_load_dwordx4 v[80:83], v6, s[20:21]
	global_load_dwordx4 v[84:87], v7, s[20:21]
	global_load_dwordx4 v[88:91], v8, s[20:21]
	global_load_dwordx4 v[56:59], v9, s[20:21]
	global_load_dwordx4 v[60:63], v9, s[20:21] offset:64
	global_load_dwordx4 v[64:67], v9, s[20:21] offset:128
	global_load_dwordx4 v[68:71], v9, s[20:21] offset:192
	s_mov_b32 s26, 2
	s_cmp_lt_u32 s26, 2
	s_cbranch_scc0 .Lri_lat_2
	s_sub_u32 s1, 1, s26
	s_cmp_lg_u32 s8, 0
	s_cselect_b32 s1, s1, s26
	s_lshl_b32 s1, s1, 7
	s_lshl_b32 s14, s10, 8
	s_add_u32 s1, s1, s14
	s_add_u32 s1, s1, 0x8000
	s_branch .Lri_rowdone_2

; __device__ __forceinline__ void ph_ret_inter(const Params& P, char* smem) {
;     ...
;       __syncthreads();
; #pragma unroll
;       for (int k_ = 0; k_ < 4; ++k_) {
;         const int i_ = tid + k_ * NTHR, t_ = i_ / 16, c8_ = i_ % 16;
;         *(h16x8*)(Qs + t_ * LDR + c8_ * 8) = rq[k_]; *(h16x8*)(Ks + t_ * LDR + c8_ * 8) = rk[k_];
;       }
;       if (tid < 256) {
;         const int t_ = tid / 2; const float w = wk[t_];
;         h16x8 o8;
; #pragma unroll
;         for (int j = 0; j < 8; ++j) o8[j] = (h16)(w * (float)rv[j]);
;         *(h16x8*)(Vs + t_ * 24 + (tid % 2) * 8) = o8;
;       }
;       if (o + 1 < RET_NCH) RI_FETCH(o + 1);
.Lri_rowdone_2:
	s_mul_i32 s14, s1, 0x3800
	s_add_u32 s20, s24, s14
	s_addc_u32 s21, s25, 0
	global_load_dwordx4 v[108:111], v4, s[20:21]
	global_load_dwordx4 v[112:115], v5, s[20:21]
	global_load_dwordx4 v[116:119], v6, s[20:21]
	global_load_dwordx4 v[120:123], v7, s[20:21]
	global_load_dwordx4 v[124:127], v8, s[20:21]
	global_load_dwordx4 v[92:95], v9, s[20:21]
	global_load_dwordx4 v[96:99], v9, s[20:21] offset:64
	global_load_dwordx4 v[100:103], v9, s[20:21] offset:128
	global_load_dwordx4 v[104:107], v9, s[20:21] offset:192
	s_waitcnt vmcnt(18)
	ds_write_b128 v10, v[36:39] offset:0
	ds_write_b128 v10, v[40:43] offset:9216
	ds_write_b128 v10, v[44:47] offset:18432
	ds_write_b128 v10, v[48:51] offset:27648
	s_cmp_gt_u32 s0, 3
	s_cbranch_scc1 .Lri_nov_0
	v_cvt_f32_f16_e32 v208, v52
	v_cvt_f32_f16_sdwa v209, v52 dst_sel:DWORD dst_unused:UNUSED_PAD src0_sel:WORD_1
	v_cvt_f32_f16_e32 v210, v53
	v_cvt_f32_f16_sdwa v211, v53 dst_sel:DWORD dst_unused:UNUSED_PAD src0_sel:WORD_1
	v_cvt_f32_f16_e32 v212, v54
	v_cvt_f32_f16_sdwa v213, v54 dst_sel:DWORD dst_unused:UNUSED_PAD src0_sel:WORD_1
	v_cvt_f32_f16_e32 v214, v55
	v_cvt_f32_f16_sdwa v215, v55 dst_sel:DWORD dst_unused:UNUSED_PAD src0_sel:WORD_1
	v_mul_f32_e32 v208, v19, v208
	v_mul_f32_e32 v209, v19, v209
	v_mul_f32_e32 v210, v19, v210
	v_mul_f32_e32 v211, v19, v211
	v_mul_f32_e32 v212, v19, v212
	v_mul_f32_e32 v213, v19, v213
	v_mul_f32_e32 v214, v19, v214
	v_mul_f32_e32 v215, v19, v215
	v_cvt_pk_f16_f32 v216, v208, v209
	v_cvt_pk_f16_f32 v217, v210, v211
	v_cvt_pk_f16_f32 v218, v212, v213
	v_cvt_pk_f16_f32 v219, v214, v215
	ds_write_b128 v11, v[216:219]

; #define MFMA16(a, b, c) emu_mfma16(a, b, c)
; #define MFMA16(a, b, c) __builtin_amdgcn_mfma_f32_16x16x32_f16(a, b, c, 0, 0, 0)
; __device__ __forceinline__ void ph_ret_inter(const Params& P, char* smem) {
;     ...
;     for (int o = 0; o < RET_NCH; ++o) {
;       const int row0 = ret_chunk_row(b, chunk_of(o));
;       const h16* Scur = St + (o & 1) * 16 * LDR;
;       h16* Snxt = St + ((o + 1) & 1) * 16 * LDR;
;       __syncthreads();
; #pragma unroll
;       for (int k_ = 0; k_ < 4; ++k_) {
;         const int i_ = tid + k_ * NTHR, t_ = i_ / 16, c8_ = i_ % 16;
;         *(h16x8*)(Qs + t_ * LDR + c8_ * 8) = rq[k_]; *(h16x8*)(Ks + t_ * LDR + c8_ * 8) = rk[k_];
;       }
;       if (tid < 256) {
;         const int t_ = tid / 2; const float w = wk[t_];
;         h16x8 o8;
; #pragma unroll
;         for (int j = 0; j < 8; ++j) o8[j] = (h16)(w * (float)rv[j]);
;         *(h16x8*)(Vs + t_ * 24 + (tid % 2) * 8) = o8;
;       }
;       if (o + 1 < RET_NCH) RI_FETCH(o + 1);
;       __syncthreads();
;       f32x4 accY = (f32x4){0.f, 0.f, 0.f, 0.f};
;       f32x4 accU = (f32x4){0.f, 0.f, 0.f, 0.f};
; #pragma unroll
;       for (int ks = 0; ks < 4; ++ks) {
;         const int ko = ks * 32 + (lane >> 4) * 8;
;         const h16x8 aq = *(const h16x8*)(Qs + (wave * 16 + (lane & 15)) * LDR + ko);
;         const h16x8 bs = *(const h16x8*)(Scur + (lane & 15) * LDR + ko);
;         accY = MFMA16(aq, bs, accY);
;         const h16x8 ak = frag_rows(Ks, LDR, ko, wave * 16 + (lane & 15));
;         const h16x8 bv = frag_rows(Vs, 24, ko, lane & 15);
;         accU = MFMA16(ak, bv, accU);
;       }
;       h16x4 sv;
; #pragma unroll
;       for (int i = 0; i < 4; ++i) {
;         const int j = wave * 16 + (lane >> 4) * 4 + i;
;         yint[((size_t)dir * NT + row0 + j) * RETW + h * RET_HD + dvs * 16 + (lane & 15)] = (h16)(accY[i] * dec[j]);
;         accS[i] = gC * accS[i] + accU[i];
;         sv[i] = (h16)accS[i];
;       }
;       *(h16x4*)(Snxt + (lane & 15) * LDR + wave * 16 + (lane >> 4) * 4) = sv;
;     }
.Lri_chunk_loop:
	s_cmp_ge_u32 s11, 0x82
	s_cbranch_scc1 .Lri_unit_done
	s_sub_u32 s1, s11, 2
	s_cmp_lt_u32 s1, 0x7c
	s_cbranch_scc1 .Lri_w_0
	s_waitcnt vmcnt(0)
.Lri_w_0:
	s_waitcnt vmcnt(13)
	s_cmp_ge_u32 s11, 0x81
	s_cbranch_scc1 .Lri_nokv_0
	ds_write_b128 v10, v[72:75] offset:36864
	ds_write_b128 v10, v[76:79] offset:46080
	ds_write_b128 v10, v[80:83] offset:55296
	ds_write_b128 v10, v[84:87] offset:64512
	s_cmp_gt_u32 s0, 3
	s_cbranch_scc1 .Lri_nov_1
	v_cvt_f32_f16_e32 v208, v88
	v_cvt_f32_f16_sdwa v209, v88 dst_sel:DWORD dst_unused:UNUSED_PAD src0_sel:WORD_1
	v_cvt_f32_f16_e32 v210, v89
	v_cvt_f32_f16_sdwa v211, v89 dst_sel:DWORD dst_unused:UNUSED_PAD src0_sel:WORD_1
	v_cvt_f32_f16_e32 v212, v90
	v_cvt_f32_f16_sdwa v213, v90 dst_sel:DWORD dst_unused:UNUSED_PAD src0_sel:WORD_1
	v_cvt_f32_f16_e32 v214, v91
	v_cvt_f32_f16_sdwa v215, v91 dst_sel:DWORD dst_unused:UNUSED_PAD src0_sel:WORD_1
	v_mul_f32_e32 v208, v19, v208
	v_mul_f32_e32 v209, v19, v209
	v_mul_f32_e32 v210, v19, v210
	v_mul_f32_e32 v211, v19, v211
	v_mul_f32_e32 v212, v19, v212
	v_mul_f32_e32 v213, v19, v213
	v_mul_f32_e32 v214, v19, v214
	v_mul_f32_e32 v215, v19, v215
	v_cvt_pk_f16_f32 v216, v208, v209
	v_cvt_pk_f16_f32 v217, v210, v211
	v_cvt_pk_f16_f32 v218, v212, v213
	v_cvt_pk_f16_f32 v219, v214, v215
	ds_write_b128 v11, v[216:219] offset:6144
.Lri_nov_1:
.Lri_nokv_0:
	s_cmp_lt_u32 s11, 2
	s_cbranch_scc0 .Lri_lat_3
	s_sub_u32 s1, 1, s11
	s_cmp_lg_u32 s8, 0
	s_cselect_b32 s1, s1, s11
	s_lshl_b32 s1, s1, 7
	s_lshl_b32 s14, s10, 8
	s_add_u32 s1, s1, s14
	s_add_u32 s1, s1, 0x8000
	s_branch .Lri_rowdone_3
.Lri_lat_3:
	s_sub_u32 s1, s11, 2
	s_sub_u32 s14, 0x81, s11
	s_cmp_lg_u32 s8, 0
	s_cselect_b32 s1, s14, s1
	s_lshl_b32 s1, s1, 7
	s_lshl_b32 s14, s10, 14
	s_add_u32 s1, s1, s14
.Lri_rowdone_3:
	s_mul_i32 s14, s8, 0x8200
	s_add_u32 s14, s14, s1
	s_lshl_b32 s15, s14, 11
	s_lshr_b32 s14, s14, 21
	s_add_u32 s28, s16, s15
	s_addc_u32 s29, s17, s14
	ds_read_b128 v[160:163], v13 offset:0
	ds_read_b64_tr_b16 v[176:177], v14 offset:0
	ds_read_b64_tr_b16 v[178:179], v14 offset:1152
	ds_read_b64_tr_b16 v[192:193], v15 offset:0
	ds_read_b64_tr_b16 v[194:195], v15 offset:192
	ds_read_b128 v[164:167], v13 offset:64
	s_waitcnt lgkmcnt(5)
	v_mfma_f32_16x16x32_f16 v[136:139], v[20:23], v[160:163], 0
	ds_read_b64_tr_b16 v[180:181], v14 offset:9216
	ds_read_b64_tr_b16 v[182:183], v14 offset:10368
	ds_read_b64_tr_b16 v[196:197], v15 offset:1536
	ds_read_b64_tr_b16 v[198:199], v15 offset:1728
	s_waitcnt lgkmcnt(5)
	v_mfma_f32_16x16x32_f16 v[140:143], v[176:179], v[192:195], 0
	ds_read_b128 v[168:171], v13 offset:128
	s_waitcnt lgkmcnt(5)
	v_mfma_f32_16x16x32_f16 v[136:139], v[24:27], v[164:167], v[136:139]
	ds_read_b64_tr_b16 v[184:185], v14 offset:18432
	ds_read_b64_tr_b16 v[186:187], v14 offset:19584
	ds_read_b64_tr_b16 v[200:201], v15 offset:3072
	ds_read_b64_tr_b16 v[202:203], v15 offset:3264
	s_waitcnt lgkmcnt(5)
	v_mfma_f32_16x16x32_f16 v[140:143], v[180:183], v[196:199], v[140:143]
	ds_read_b128 v[172:175], v13 offset:192
	s_waitcnt lgkmcnt(5)
	v_mfma_f32_16x16x32_f16 v[136:139], v[28:31], v[168:171], v[136:139]
	ds_read_b64_tr_b16 v[188:189], v14 offset:27648
	ds_read_b64_tr_b16 v[190:191], v14 offset:28800
	ds_read_b64_tr_b16 v[204:205], v15 offset:4608
	ds_read_b64_tr_b16 v[206:207], v15 offset:4800
	s_waitcnt lgkmcnt(5)
	v_mfma_f32_16x16x32_f16 v[140:143], v[184:187], v[200:203], v[140:143]
	s_waitcnt lgkmcnt(4)
	v_mfma_f32_16x16x32_f16 v[136:139], v[32:35], v[172:175], v[136:139]
	s_waitcnt lgkmcnt(0)
	v_mfma_f32_16x16x32_f16 v[140:143], v[188:191], v[204:207], v[140:143]
	s_nop 7
	s_nop 1
	v_mul_f32_e32 v208, v136, v128
	v_mul_f32_e32 v209, v137, v129
	v_mul_f32_e32 v210, v138, v130
	v_mul_f32_e32 v211, v139, v131
	v_cvt_f16_f32_e32 v208, v208
	v_cvt_f16_f32_e32 v209, v209
	v_cvt_f16_f32_e32 v210, v210
	v_cvt_f16_f32_e32 v211, v211
	global_store_short v17, v208, s[28:29]
	global_store_short v17, v209, s[28:29] offset:2048
	global_store_short v18, v210, s[28:29]
	global_store_short v18, v211, s[28:29] offset:2048
	v_fma_f32 v132, s13, v132, v140
	v_fma_f32 v133, s13, v133, v141
	v_fma_f32 v134, s13, v134, v142
	v_fma_f32 v135, s13, v135, v143
	v_cvt_pk_f16_f32 v212, v132, v133
	v_cvt_pk_f16_f32 v213, v134, v135
	ds_write_b64 v16, v[212:213] offset:4352
	s_add_u32 s26, s11, 3
	s_cmp_ge_u32 s26, 0x82
	s_cbranch_scc1 .Lri_nopf_0
	s_cmp_lt_u32 s26, 2
	s_cbranch_scc0 .Lri_lat_4
	s_sub_u32 s1, 1, s26
	s_cmp_lg_u32 s8, 0
	s_cselect_b32 s1, s1, s26
	s_lshl_b32 s1, s1, 7
	s_lshl_b32 s14, s10, 8
	s_add_u32 s1, s1, s14
	s_add_u32 s1, s1, 0x8000
	s_branch .Lri_rowdone_4

; __device__ __forceinline__ void ph_ret_inter(const Params& P, char* smem) {
;     ...
;     for (int o = 0; o < RET_NCH; ++o) {
;       const int row0 = ret_chunk_row(b, chunk_of(o));
;       const h16* Scur = St + (o & 1) * 16 * LDR;
;       h16* Snxt = St + ((o + 1) & 1) * 16 * LDR;
;       __syncthreads();
; #pragma unroll
;       for (int k_ = 0; k_ < 4; ++k_) {
;         const int i_ = tid + k_ * NTHR, t_ = i_ / 16, c8_ = i_ % 16;
;         *(h16x8*)(Qs + t_ * LDR + c8_ * 8) = rq[k_]; *(h16x8*)(Ks + t_ * LDR + c8_ * 8) = rk[k_];
;       }
;       if (tid < 256) {
;         const int t_ = tid / 2; const float w = wk[t_];
;         h16x8 o8;
; #pragma unroll
;         for (int j = 0; j < 8; ++j) o8[j] = (h16)(w * (float)rv[j]);
;         *(h16x8*)(Vs + t_ * 24 + (tid % 2) * 8) = o8;
;       }
;       if (o + 1 < RET_NCH) RI_FETCH(o + 1);
.Lri_rowdone_4:
	s_mul_i32 s14, s1, 0x3800
	s_add_u32 s20, s24, s14
	s_addc_u32 s21, s25, 0
	global_load_dwordx4 v[36:39], v4, s[20:21]
	global_load_dwordx4 v[40:43], v5, s[20:21]
	global_load_dwordx4 v[44:47], v6, s[20:21]
	global_load_dwordx4 v[48:51], v7, s[20:21]
	global_load_dwordx4 v[52:55], v8, s[20:21]
	global_load_dwordx4 v[20:23], v9, s[20:21]
	global_load_dwordx4 v[24:27], v9, s[20:21] offset:64
	global_load_dwordx4 v[28:31], v9, s[20:21] offset:128
	global_load_dwordx4 v[32:35], v9, s[20:21] offset:192
.Lri_nopf_0:
	s_add_u32 s11, s11, 1
	s_waitcnt lgkmcnt(0)
	s_barrier
	s_cmp_ge_u32 s11, 0x82
	s_cbranch_scc1 .Lri_unit_done
	s_sub_u32 s1, s11, 2
	s_cmp_lt_u32 s1, 0x7c
	s_cbranch_scc1 .Lri_w_1
	s_waitcnt vmcnt(0)
.Lri_w_1:
	s_waitcnt vmcnt(13)
	s_cmp_ge_u32 s11, 0x81
	s_cbranch_scc1 .Lri_nokv_1
	ds_write_b128 v10, v[108:111] offset:0
	ds_write_b128 v10, v[112:115] offset:9216
	ds_write_b128 v10, v[116:119] offset:18432
	ds_write_b128 v10, v[120:123] offset:27648
	s_cmp_gt_u32 s0, 3
	s_cbranch_scc1 .Lri_nov_2
	v_cvt_f32_f16_e32 v208, v124
	v_cvt_f32_f16_sdwa v209, v124 dst_sel:DWORD dst_unused:UNUSED_PAD src0_sel:WORD_1
	v_cvt_f32_f16_e32 v210, v125
	v_cvt_f32_f16_sdwa v211, v125 dst_sel:DWORD dst_unused:UNUSED_PAD src0_sel:WORD_1
	v_cvt_f32_f16_e32 v212, v126
	v_cvt_f32_f16_sdwa v213, v126 dst_sel:DWORD dst_unused:UNUSED_PAD src0_sel:WORD_1
	v_cvt_f32_f16_e32 v214, v127
	v_cvt_f32_f16_sdwa v215, v127 dst_sel:DWORD dst_unused:UNUSED_PAD src0_sel:WORD_1
	v_mul_f32_e32 v208, v19, v208
	v_mul_f32_e32 v209, v19, v209
	v_mul_f32_e32 v210, v19, v210
	v_mul_f32_e32 v211, v19, v211
	v_mul_f32_e32 v212, v19, v212
	v_mul_f32_e32 v213, v19, v213
	v_mul_f32_e32 v214, v19, v214
	v_mul_f32_e32 v215, v19, v215
	v_cvt_pk_f16_f32 v216, v208, v209
	v_cvt_pk_f16_f32 v217, v210, v211
	v_cvt_pk_f16_f32 v218, v212, v213
	v_cvt_pk_f16_f32 v219, v214, v215
	ds_write_b128 v11, v[216:219]

; #define MFMA16(a, b, c) emu_mfma16(a, b, c)
; #define MFMA16(a, b, c) __builtin_amdgcn_mfma_f32_16x16x32_f16(a, b, c, 0, 0, 0)
; __device__ __forceinline__ void ph_ret_inter(const Params& P, char* smem) {
;     ...
;       f32x4 accY = (f32x4){0.f, 0.f, 0.f, 0.f};
;       f32x4 accU = (f32x4){0.f, 0.f, 0.f, 0.f};
; #pragma unroll
;       for (int ks = 0; ks < 4; ++ks) {
;         const int ko = ks * 32 + (lane >> 4) * 8;
;         const h16x8 aq = *(const h16x8*)(Qs + (wave * 16 + (lane & 15)) * LDR + ko);
;         const h16x8 bs = *(const h16x8*)(Scur + (lane & 15) * LDR + ko);
;         accY = MFMA16(aq, bs, accY);
;         const h16x8 ak = frag_rows(Ks, LDR, ko, wave * 16 + (lane & 15));
;         const h16x8 bv = frag_rows(Vs, 24, ko, lane & 15);
;         accU = MFMA16(ak, bv, accU);
;       }
;       h16x4 sv;
; #pragma unroll
;       for (int i = 0; i < 4; ++i) {
;         const int j = wave * 16 + (lane >> 4) * 4 + i;
;         yint[((size_t)dir * NT + row0 + j) * RETW + h * RET_HD + dvs * 16 + (lane & 15)] = (h16)(accY[i] * dec[j]);
;         accS[i] = gC * accS[i] + accU[i];
;         sv[i] = (h16)accS[i];
;       }
;       *(h16x4*)(Snxt + (lane & 15) * LDR + wave * 16 + (lane >> 4) * 4) = sv;
;     }
.Lri_rowdone_5:
	s_mul_i32 s14, s8, 0x8200
	s_add_u32 s14, s14, s1
	s_lshl_b32 s15, s14, 11
	s_lshr_b32 s14, s14, 21
	s_add_u32 s28, s16, s15
	s_addc_u32 s29, s17, s14
	ds_read_b128 v[160:163], v13 offset:4352
	ds_read_b64_tr_b16 v[176:177], v12 offset:0
	ds_read_b64_tr_b16 v[178:179], v12 offset:1152
	ds_read_b64_tr_b16 v[192:193], v15 offset:6144
	ds_read_b64_tr_b16 v[194:195], v15 offset:6336
	ds_read_b128 v[164:167], v13 offset:4416
	s_waitcnt lgkmcnt(5)
	v_mfma_f32_16x16x32_f16 v[136:139], v[56:59], v[160:163], 0
	ds_read_b64_tr_b16 v[180:181], v12 offset:9216
	ds_read_b64_tr_b16 v[182:183], v12 offset:10368
	ds_read_b64_tr_b16 v[196:197], v15 offset:7680
	ds_read_b64_tr_b16 v[198:199], v15 offset:7872
	s_waitcnt lgkmcnt(5)
	v_mfma_f32_16x16x32_f16 v[140:143], v[176:179], v[192:195], 0
	ds_read_b128 v[168:171], v13 offset:4480
	s_waitcnt lgkmcnt(5)
	v_mfma_f32_16x16x32_f16 v[136:139], v[60:63], v[164:167], v[136:139]
	ds_read_b64_tr_b16 v[184:185], v12 offset:18432
	ds_read_b64_tr_b16 v[186:187], v12 offset:19584
	ds_read_b64_tr_b16 v[200:201], v15 offset:9216
	ds_read_b64_tr_b16 v[202:203], v15 offset:9408
	s_waitcnt lgkmcnt(5)
	v_mfma_f32_16x16x32_f16 v[140:143], v[180:183], v[196:199], v[140:143]
	ds_read_b128 v[172:175], v13 offset:4544
	s_waitcnt lgkmcnt(5)
	v_mfma_f32_16x16x32_f16 v[136:139], v[64:67], v[168:171], v[136:139]
	ds_read_b64_tr_b16 v[188:189], v12 offset:27648
	ds_read_b64_tr_b16 v[190:191], v12 offset:28800
	ds_read_b64_tr_b16 v[204:205], v15 offset:10752
	ds_read_b64_tr_b16 v[206:207], v15 offset:10944
	s_waitcnt lgkmcnt(5)
	v_mfma_f32_16x16x32_f16 v[140:143], v[184:187], v[200:203], v[140:143]
	s_waitcnt lgkmcnt(4)
	v_mfma_f32_16x16x32_f16 v[136:139], v[68:71], v[172:175], v[136:139]
	s_waitcnt lgkmcnt(0)
	v_mfma_f32_16x16x32_f16 v[140:143], v[188:191], v[204:207], v[140:143]
	s_nop 7
	s_nop 1
	v_mul_f32_e32 v208, v136, v128
	v_mul_f32_e32 v209, v137, v129
	v_mul_f32_e32 v210, v138, v130
	v_mul_f32_e32 v211, v139, v131
	v_cvt_f16_f32_e32 v208, v208
	v_cvt_f16_f32_e32 v209, v209
	v_cvt_f16_f32_e32 v210, v210
	v_cvt_f16_f32_e32 v211, v211
	global_store_short v17, v208, s[28:29]
	global_store_short v17, v209, s[28:29] offset:2048
	global_store_short v18, v210, s[28:29]
	global_store_short v18, v211, s[28:29] offset:2048
	v_fma_f32 v132, s13, v132, v140
	v_fma_f32 v133, s13, v133, v141
	v_fma_f32 v134, s13, v134, v142
	v_fma_f32 v135, s13, v135, v143
	v_cvt_pk_f16_f32 v212, v132, v133
	v_cvt_pk_f16_f32 v213, v134, v135
	ds_write_b64 v16, v[212:213] offset:0
	s_add_u32 s26, s11, 3
	s_cmp_ge_u32 s26, 0x82
	s_cbranch_scc1 .Lri_nopf_1
	s_cmp_lt_u32 s26, 2
	s_cbranch_scc0 .Lri_lat_6
	s_sub_u32 s1, 1, s26
	s_cmp_lg_u32 s8, 0
	s_cselect_b32 s1, s1, s26
	s_lshl_b32 s1, s1, 7
	s_lshl_b32 s14, s10, 8
	s_add_u32 s1, s1, s14
	s_add_u32 s1, s1, 0x8000
	s_branch .Lri_rowdone_6

.Lri_rowdone_6:
	s_mul_i32 s14, s1, 0x3800
	s_add_u32 s20, s24, s14
	s_addc_u32 s21, s25, 0
	global_load_dwordx4 v[72:75], v4, s[20:21]
	global_load_dwordx4 v[76:79], v5, s[20:21]
	global_load_dwordx4 v[80:83], v6, s[20:21]
	global_load_dwordx4 v[84:87], v7, s[20:21]
	global_load_dwordx4 v[88:91], v8, s[20:21]
	global_load_dwordx4 v[56:59], v9, s[20:21]
	global_load_dwordx4 v[60:63], v9, s[20:21] offset:64
	global_load_dwordx4 v[64:67], v9, s[20:21] offset:128
	global_load_dwordx4 v[68:71], v9, s[20:21] offset:192

; __device__ __forceinline__ void ph_ret_inter(const Params& P, char* smem) {
;     ...
;       __syncthreads();
; #pragma unroll
;       for (int k_ = 0; k_ < 4; ++k_) {
;         const int i_ = tid + k_ * NTHR, t_ = i_ / 16, c8_ = i_ % 16;
;         *(h16x8*)(Qs + t_ * LDR + c8_ * 8) = rq[k_]; *(h16x8*)(Ks + t_ * LDR + c8_ * 8) = rk[k_];
;       }
;       if (tid < 256) {
;         const int t_ = tid / 2; const float w = wk[t_];
;         h16x8 o8;
; #pragma unroll
;         for (int j = 0; j < 8; ++j) o8[j] = (h16)(w * (float)rv[j]);
;         *(h16x8*)(Vs + t_ * 24 + (tid % 2) * 8) = o8;
;       }
.Lri_w_2:
	s_waitcnt vmcnt(13)
	s_cmp_ge_u32 s11, 0x81
	s_cbranch_scc1 .Lri_nokv_2
	ds_write_b128 v10, v[36:39] offset:36864
	ds_write_b128 v10, v[40:43] offset:46080
	ds_write_b128 v10, v[44:47] offset:55296
	ds_write_b128 v10, v[48:51] offset:64512
	s_cmp_gt_u32 s0, 3
	s_cbranch_scc1 .Lri_nov_3
	v_cvt_f32_f16_e32 v208, v52
	v_cvt_f32_f16_sdwa v209, v52 dst_sel:DWORD dst_unused:UNUSED_PAD src0_sel:WORD_1
	v_cvt_f32_f16_e32 v210, v53
	v_cvt_f32_f16_sdwa v211, v53 dst_sel:DWORD dst_unused:UNUSED_PAD src0_sel:WORD_1
	v_cvt_f32_f16_e32 v212, v54
	v_cvt_f32_f16_sdwa v213, v54 dst_sel:DWORD dst_unused:UNUSED_PAD src0_sel:WORD_1
	v_cvt_f32_f16_e32 v214, v55
	v_cvt_f32_f16_sdwa v215, v55 dst_sel:DWORD dst_unused:UNUSED_PAD src0_sel:WORD_1
	v_mul_f32_e32 v208, v19, v208
	v_mul_f32_e32 v209, v19, v209
	v_mul_f32_e32 v210, v19, v210
	v_mul_f32_e32 v211, v19, v211
	v_mul_f32_e32 v212, v19, v212
	v_mul_f32_e32 v213, v19, v213
	v_mul_f32_e32 v214, v19, v214
	v_mul_f32_e32 v215, v19, v215
	v_cvt_pk_f16_f32 v216, v208, v209
	v_cvt_pk_f16_f32 v217, v210, v211
	v_cvt_pk_f16_f32 v218, v212, v213
	v_cvt_pk_f16_f32 v219, v214, v215
	ds_write_b128 v11, v[216:219] offset:6144

; #define MFMA16(a, b, c) emu_mfma16(a, b, c)
; #define MFMA16(a, b, c) __builtin_amdgcn_mfma_f32_16x16x32_f16(a, b, c, 0, 0, 0)
; __device__ __forceinline__ void ph_ret_inter(const Params& P, char* smem) {
;     ...
;       f32x4 accY = (f32x4){0.f, 0.f, 0.f, 0.f};
;       f32x4 accU = (f32x4){0.f, 0.f, 0.f, 0.f};
; #pragma unroll
;       for (int ks = 0; ks < 4; ++ks) {
;         const int ko = ks * 32 + (lane >> 4) * 8;
;         const h16x8 aq = *(const h16x8*)(Qs + (wave * 16 + (lane & 15)) * LDR + ko);
;         const h16x8 bs = *(const h16x8*)(Scur + (lane & 15) * LDR + ko);
;         accY = MFMA16(aq, bs, accY);
;         const h16x8 ak = frag_rows(Ks, LDR, ko, wave * 16 + (lane & 15));
;         const h16x8 bv = frag_rows(Vs, 24, ko, lane & 15);
;         accU = MFMA16(ak, bv, accU);
;       }
;       h16x4 sv;
; #pragma unroll
;       for (int i = 0; i < 4; ++i) {
;         const int j = wave * 16 + (lane >> 4) * 4 + i;
;         yint[((size_t)dir * NT + row0 + j) * RETW + h * RET_HD + dvs * 16 + (lane & 15)] = (h16)(accY[i] * dec[j]);
;         accS[i] = gC * accS[i] + accU[i];
;         sv[i] = (h16)accS[i];
;       }
;       *(h16x4*)(Snxt + (lane & 15) * LDR + wave * 16 + (lane >> 4) * 4) = sv;
;     }
.Lri_rowdone_7:
	s_mul_i32 s14, s8, 0x8200
	s_add_u32 s14, s14, s1
	s_lshl_b32 s15, s14, 11
	s_lshr_b32 s14, s14, 21
	s_add_u32 s28, s16, s15
	s_addc_u32 s29, s17, s14
	ds_read_b128 v[160:163], v13 offset:0
	ds_read_b64_tr_b16 v[176:177], v14 offset:0
	ds_read_b64_tr_b16 v[178:179], v14 offset:1152
	ds_read_b64_tr_b16 v[192:193], v15 offset:0
	ds_read_b64_tr_b16 v[194:195], v15 offset:192
	ds_read_b128 v[164:167], v13 offset:64
	s_waitcnt lgkmcnt(5)
	v_mfma_f32_16x16x32_f16 v[136:139], v[92:95], v[160:163], 0
	ds_read_b64_tr_b16 v[180:181], v14 offset:9216
	ds_read_b64_tr_b16 v[182:183], v14 offset:10368
	ds_read_b64_tr_b16 v[196:197], v15 offset:1536
	ds_read_b64_tr_b16 v[198:199], v15 offset:1728
	s_waitcnt lgkmcnt(5)
	v_mfma_f32_16x16x32_f16 v[140:143], v[176:179], v[192:195], 0
	ds_read_b128 v[168:171], v13 offset:128
	s_waitcnt lgkmcnt(5)
	v_mfma_f32_16x16x32_f16 v[136:139], v[96:99], v[164:167], v[136:139]
	ds_read_b64_tr_b16 v[184:185], v14 offset:18432
	ds_read_b64_tr_b16 v[186:187], v14 offset:19584
	ds_read_b64_tr_b16 v[200:201], v15 offset:3072
	ds_read_b64_tr_b16 v[202:203], v15 offset:3264
	s_waitcnt lgkmcnt(5)
	v_mfma_f32_16x16x32_f16 v[140:143], v[180:183], v[196:199], v[140:143]
	ds_read_b128 v[172:175], v13 offset:192
	s_waitcnt lgkmcnt(5)
	v_mfma_f32_16x16x32_f16 v[136:139], v[100:103], v[168:171], v[136:139]
	ds_read_b64_tr_b16 v[188:189], v14 offset:27648
	ds_read_b64_tr_b16 v[190:191], v14 offset:28800
	ds_read_b64_tr_b16 v[204:205], v15 offset:4608
	ds_read_b64_tr_b16 v[206:207], v15 offset:4800
	s_waitcnt lgkmcnt(5)
	v_mfma_f32_16x16x32_f16 v[140:143], v[184:187], v[200:203], v[140:143]
	s_waitcnt lgkmcnt(4)
	v_mfma_f32_16x16x32_f16 v[136:139], v[104:107], v[172:175], v[136:139]
	s_waitcnt lgkmcnt(0)
	v_mfma_f32_16x16x32_f16 v[140:143], v[188:191], v[204:207], v[140:143]
	s_nop 7
	s_nop 1
	v_mul_f32_e32 v208, v136, v128
	v_mul_f32_e32 v209, v137, v129
	v_mul_f32_e32 v210, v138, v130
	v_mul_f32_e32 v211, v139, v131
	v_cvt_f16_f32_e32 v208, v208
	v_cvt_f16_f32_e32 v209, v209
	v_cvt_f16_f32_e32 v210, v210
	v_cvt_f16_f32_e32 v211, v211
	global_store_short v17, v208, s[28:29]
	global_store_short v17, v209, s[28:29] offset:2048
	global_store_short v18, v210, s[28:29]
	global_store_short v18, v211, s[28:29] offset:2048
	v_fma_f32 v132, s13, v132, v140
	v_fma_f32 v133, s13, v133, v141
	v_fma_f32 v134, s13, v134, v142
	v_fma_f32 v135, s13, v135, v143
	v_cvt_pk_f16_f32 v212, v132, v133
	v_cvt_pk_f16_f32 v213, v134, v135
	ds_write_b64 v16, v[212:213] offset:4352
	s_add_u32 s26, s11, 3
	s_cmp_ge_u32 s26, 0x82
	s_cbranch_scc1 .Lri_nopf_2
	s_cmp_lt_u32 s26, 2
	s_cbranch_scc0 .Lri_lat_8
	s_sub_u32 s1, 1, s26
	s_cmp_lg_u32 s8, 0
	s_cselect_b32 s1, s1, s26
	s_lshl_b32 s1, s1, 7
	s_lshl_b32 s14, s10, 8
	s_add_u32 s1, s1, s14
	s_add_u32 s1, s1, 0x8000
	s_branch .Lri_rowdone_8

.Lri_rowdone_8:
	s_mul_i32 s14, s1, 0x3800
	s_add_u32 s20, s24, s14
	s_addc_u32 s21, s25, 0
	global_load_dwordx4 v[108:111], v4, s[20:21]
	global_load_dwordx4 v[112:115], v5, s[20:21]
	global_load_dwordx4 v[116:119], v6, s[20:21]
	global_load_dwordx4 v[120:123], v7, s[20:21]
	global_load_dwordx4 v[124:127], v8, s[20:21]
	global_load_dwordx4 v[92:95], v9, s[20:21]
	global_load_dwordx4 v[96:99], v9, s[20:21] offset:64
	global_load_dwordx4 v[100:103], v9, s[20:21] offset:128
	global_load_dwordx4 v[104:107], v9, s[20:21] offset:192

; __device__ __forceinline__ void ph_ret_inter(const Params& P, char* smem) {
;     ...
;       __syncthreads();
; #pragma unroll
;       for (int k_ = 0; k_ < 4; ++k_) {
;         const int i_ = tid + k_ * NTHR, t_ = i_ / 16, c8_ = i_ % 16;
;         *(h16x8*)(Qs + t_ * LDR + c8_ * 8) = rq[k_]; *(h16x8*)(Ks + t_ * LDR + c8_ * 8) = rk[k_];
;       }
;       if (tid < 256) {
;         const int t_ = tid / 2; const float w = wk[t_];
;         h16x8 o8;
; #pragma unroll
;         for (int j = 0; j < 8; ++j) o8[j] = (h16)(w * (float)rv[j]);
;         *(h16x8*)(Vs + t_ * 24 + (tid % 2) * 8) = o8;
;       }
.Lri_w_3:
	s_waitcnt vmcnt(13)
	s_cmp_ge_u32 s11, 0x81
	s_cbranch_scc1 .Lri_nokv_3
	ds_write_b128 v10, v[72:75] offset:0
	ds_write_b128 v10, v[76:79] offset:9216
	ds_write_b128 v10, v[80:83] offset:18432
	ds_write_b128 v10, v[84:87] offset:27648
	s_cmp_gt_u32 s0, 3
	s_cbranch_scc1 .Lri_nov_4
	v_cvt_f32_f16_e32 v208, v88
	v_cvt_f32_f16_sdwa v209, v88 dst_sel:DWORD dst_unused:UNUSED_PAD src0_sel:WORD_1
	v_cvt_f32_f16_e32 v210, v89
	v_cvt_f32_f16_sdwa v211, v89 dst_sel:DWORD dst_unused:UNUSED_PAD src0_sel:WORD_1
	v_cvt_f32_f16_e32 v212, v90
	v_cvt_f32_f16_sdwa v213, v90 dst_sel:DWORD dst_unused:UNUSED_PAD src0_sel:WORD_1
	v_cvt_f32_f16_e32 v214, v91
	v_cvt_f32_f16_sdwa v215, v91 dst_sel:DWORD dst_unused:UNUSED_PAD src0_sel:WORD_1
	v_mul_f32_e32 v208, v19, v208
	v_mul_f32_e32 v209, v19, v209
	v_mul_f32_e32 v210, v19, v210
	v_mul_f32_e32 v211, v19, v211
	v_mul_f32_e32 v212, v19, v212
	v_mul_f32_e32 v213, v19, v213
	v_mul_f32_e32 v214, v19, v214
	v_mul_f32_e32 v215, v19, v215
	v_cvt_pk_f16_f32 v216, v208, v209
	v_cvt_pk_f16_f32 v217, v210, v211
	v_cvt_pk_f16_f32 v218, v212, v213
	v_cvt_pk_f16_f32 v219, v214, v215
	ds_write_b128 v11, v[216:219]

; #define MFMA16(a, b, c) emu_mfma16(a, b, c)
; #define MFMA16(a, b, c) __builtin_amdgcn_mfma_f32_16x16x32_f16(a, b, c, 0, 0, 0)
; __device__ __forceinline__ void ph_ret_inter(const Params& P, char* smem) {
;     ...
;       f32x4 accY = (f32x4){0.f, 0.f, 0.f, 0.f};
;       f32x4 accU = (f32x4){0.f, 0.f, 0.f, 0.f};
; #pragma unroll
;       for (int ks = 0; ks < 4; ++ks) {
;         const int ko = ks * 32 + (lane >> 4) * 8;
;         const h16x8 aq = *(const h16x8*)(Qs + (wave * 16 + (lane & 15)) * LDR + ko);
;         const h16x8 bs = *(const h16x8*)(Scur + (lane & 15) * LDR + ko);
;         accY = MFMA16(aq, bs, accY);
;         const h16x8 ak = frag_rows(Ks, LDR, ko, wave * 16 + (lane & 15));
;         const h16x8 bv = frag_rows(Vs, 24, ko, lane & 15);
;         accU = MFMA16(ak, bv, accU);
;       }
;       h16x4 sv;
; #pragma unroll
;       for (int i = 0; i < 4; ++i) {
;         const int j = wave * 16 + (lane >> 4) * 4 + i;
;         yint[((size_t)dir * NT + row0 + j) * RETW + h * RET_HD + dvs * 16 + (lane & 15)] = (h16)(accY[i] * dec[j]);
;         accS[i] = gC * accS[i] + accU[i];
;         sv[i] = (h16)accS[i];
;       }
;       *(h16x4*)(Snxt + (lane & 15) * LDR + wave * 16 + (lane >> 4) * 4) = sv;
;     }
.Lri_rowdone_9:
	s_mul_i32 s14, s8, 0x8200
	s_add_u32 s14, s14, s1
	s_lshl_b32 s15, s14, 11
	s_lshr_b32 s14, s14, 21
	s_add_u32 s28, s16, s15
	s_addc_u32 s29, s17, s14
	ds_read_b128 v[160:163], v13 offset:4352
	ds_read_b64_tr_b16 v[176:177], v12 offset:0
	ds_read_b64_tr_b16 v[178:179], v12 offset:1152
	ds_read_b64_tr_b16 v[192:193], v15 offset:6144
	ds_read_b64_tr_b16 v[194:195], v15 offset:6336
	ds_read_b128 v[164:167], v13 offset:4416
	s_waitcnt lgkmcnt(5)
	v_mfma_f32_16x16x32_f16 v[136:139], v[20:23], v[160:163], 0
	ds_read_b64_tr_b16 v[180:181], v12 offset:9216
	ds_read_b64_tr_b16 v[182:183], v12 offset:10368
	ds_read_b64_tr_b16 v[196:197], v15 offset:7680
	ds_read_b64_tr_b16 v[198:199], v15 offset:7872
	s_waitcnt lgkmcnt(5)
	v_mfma_f32_16x16x32_f16 v[140:143], v[176:179], v[192:195], 0
	ds_read_b128 v[168:171], v13 offset:4480
	s_waitcnt lgkmcnt(5)
	v_mfma_f32_16x16x32_f16 v[136:139], v[24:27], v[164:167], v[136:139]
	ds_read_b64_tr_b16 v[184:185], v12 offset:18432
	ds_read_b64_tr_b16 v[186:187], v12 offset:19584
	ds_read_b64_tr_b16 v[200:201], v15 offset:9216
	ds_read_b64_tr_b16 v[202:203], v15 offset:9408
	s_waitcnt lgkmcnt(5)
	v_mfma_f32_16x16x32_f16 v[140:143], v[180:183], v[196:199], v[140:143]
	ds_read_b128 v[172:175], v13 offset:4544
	s_waitcnt lgkmcnt(5)
	v_mfma_f32_16x16x32_f16 v[136:139], v[28:31], v[168:171], v[136:139]
	ds_read_b64_tr_b16 v[188:189], v12 offset:27648
	ds_read_b64_tr_b16 v[190:191], v12 offset:28800
	ds_read_b64_tr_b16 v[204:205], v15 offset:10752
	ds_read_b64_tr_b16 v[206:207], v15 offset:10944
	s_waitcnt lgkmcnt(5)
	v_mfma_f32_16x16x32_f16 v[140:143], v[184:187], v[200:203], v[140:143]
	s_waitcnt lgkmcnt(4)
	v_mfma_f32_16x16x32_f16 v[136:139], v[32:35], v[172:175], v[136:139]
	s_waitcnt lgkmcnt(0)
	v_mfma_f32_16x16x32_f16 v[140:143], v[188:191], v[204:207], v[140:143]
	s_nop 7
	s_nop 1
	v_mul_f32_e32 v208, v136, v128
	v_mul_f32_e32 v209, v137, v129
	v_mul_f32_e32 v210, v138, v130
	v_mul_f32_e32 v211, v139, v131
	v_cvt_f16_f32_e32 v208, v208
	v_cvt_f16_f32_e32 v209, v209
	v_cvt_f16_f32_e32 v210, v210
	v_cvt_f16_f32_e32 v211, v211
	global_store_short v17, v208, s[28:29]
	global_store_short v17, v209, s[28:29] offset:2048
	global_store_short v18, v210, s[28:29]
	global_store_short v18, v211, s[28:29] offset:2048
	v_fma_f32 v132, s13, v132, v140
	v_fma_f32 v133, s13, v133, v141
	v_fma_f32 v134, s13, v134, v142
	v_fma_f32 v135, s13, v135, v143
	v_cvt_pk_f16_f32 v212, v132, v133
	v_cvt_pk_f16_f32 v213, v134, v135
	ds_write_b64 v16, v[212:213] offset:0
	s_add_u32 s26, s11, 3
	s_cmp_ge_u32 s26, 0x82
	s_cbranch_scc1 .Lri_nopf_3
	s_cmp_lt_u32 s26, 2
	s_cbranch_scc0 .Lri_lat_10
	s_sub_u32 s1, 1, s26
	s_cmp_lg_u32 s8, 0
	s_cselect_b32 s1, s1, s26
	s_lshl_b32 s1, s1, 7
	s_lshl_b32 s14, s10, 8
	s_add_u32 s1, s1, s14
	s_add_u32 s1, s1, 0x8000
	s_branch .Lri_rowdone_10

; __device__ __forceinline__ void ph_ret_inter(const Params& P, char* smem) {
;     ...
;       __syncthreads();
; #pragma unroll
;       for (int k_ = 0; k_ < 4; ++k_) {
;         const int i_ = tid + k_ * NTHR, t_ = i_ / 16, c8_ = i_ % 16;
;         *(h16x8*)(Qs + t_ * LDR + c8_ * 8) = rq[k_]; *(h16x8*)(Ks + t_ * LDR + c8_ * 8) = rk[k_];
;       }
;       if (tid < 256) {
;         const int t_ = tid / 2; const float w = wk[t_];
;         h16x8 o8;
; #pragma unroll
;         for (int j = 0; j < 8; ++j) o8[j] = (h16)(w * (float)rv[j]);
;         *(h16x8*)(Vs + t_ * 24 + (tid % 2) * 8) = o8;
;       }
.Lri_w_4:
	s_waitcnt vmcnt(13)
	s_cmp_ge_u32 s11, 0x81
	s_cbranch_scc1 .Lri_nokv_4
	ds_write_b128 v10, v[108:111] offset:36864
	ds_write_b128 v10, v[112:115] offset:46080
	ds_write_b128 v10, v[116:119] offset:55296
	ds_write_b128 v10, v[120:123] offset:64512
	s_cmp_gt_u32 s0, 3
	s_cbranch_scc1 .Lri_nov_5
	v_cvt_f32_f16_e32 v208, v124
	v_cvt_f32_f16_sdwa v209, v124 dst_sel:DWORD dst_unused:UNUSED_PAD src0_sel:WORD_1
	v_cvt_f32_f16_e32 v210, v125
	v_cvt_f32_f16_sdwa v211, v125 dst_sel:DWORD dst_unused:UNUSED_PAD src0_sel:WORD_1
	v_cvt_f32_f16_e32 v212, v126
	v_cvt_f32_f16_sdwa v213, v126 dst_sel:DWORD dst_unused:UNUSED_PAD src0_sel:WORD_1
	v_cvt_f32_f16_e32 v214, v127
	v_cvt_f32_f16_sdwa v215, v127 dst_sel:DWORD dst_unused:UNUSED_PAD src0_sel:WORD_1
	v_mul_f32_e32 v208, v19, v208
	v_mul_f32_e32 v209, v19, v209
	v_mul_f32_e32 v210, v19, v210
	v_mul_f32_e32 v211, v19, v211
	v_mul_f32_e32 v212, v19, v212
	v_mul_f32_e32 v213, v19, v213
	v_mul_f32_e32 v214, v19, v214
	v_mul_f32_e32 v215, v19, v215
	v_cvt_pk_f16_f32 v216, v208, v209
	v_cvt_pk_f16_f32 v217, v210, v211
	v_cvt_pk_f16_f32 v218, v212, v213
	v_cvt_pk_f16_f32 v219, v214, v215
	ds_write_b128 v11, v[216:219] offset:6144

; #define MFMA16(a, b, c) emu_mfma16(a, b, c)
; #define MFMA16(a, b, c) __builtin_amdgcn_mfma_f32_16x16x32_f16(a, b, c, 0, 0, 0)
; __device__ __forceinline__ void ph_ret_inter(const Params& P, char* smem) {
;     ...
;       f32x4 accY = (f32x4){0.f, 0.f, 0.f, 0.f};
;       f32x4 accU = (f32x4){0.f, 0.f, 0.f, 0.f};
; #pragma unroll
;       for (int ks = 0; ks < 4; ++ks) {
;         const int ko = ks * 32 + (lane >> 4) * 8;
;         const h16x8 aq = *(const h16x8*)(Qs + (wave * 16 + (lane & 15)) * LDR + ko);
;         const h16x8 bs = *(const h16x8*)(Scur + (lane & 15) * LDR + ko);
;         accY = MFMA16(aq, bs, accY);
;         const h16x8 ak = frag_rows(Ks, LDR, ko, wave * 16 + (lane & 15));
;         const h16x8 bv = frag_rows(Vs, 24, ko, lane & 15);
;         accU = MFMA16(ak, bv, accU);
;       }
;       h16x4 sv;
; #pragma unroll
;       for (int i = 0; i < 4; ++i) {
;         const int j = wave * 16 + (lane >> 4) * 4 + i;
;         yint[((size_t)dir * NT + row0 + j) * RETW + h * RET_HD + dvs * 16 + (lane & 15)] = (h16)(accY[i] * dec[j]);
;         accS[i] = gC * accS[i] + accU[i];
;         sv[i] = (h16)accS[i];
;       }
;       *(h16x4*)(Snxt + (lane & 15) * LDR + wave * 16 + (lane >> 4) * 4) = sv;
;     }
.Lri_rowdone_11:
	s_mul_i32 s14, s8, 0x8200
	s_add_u32 s14, s14, s1
	s_lshl_b32 s15, s14, 11
	s_lshr_b32 s14, s14, 21
	s_add_u32 s28, s16, s15
	s_addc_u32 s29, s17, s14
	ds_read_b128 v[160:163], v13 offset:0
	ds_read_b64_tr_b16 v[176:177], v14 offset:0
	ds_read_b64_tr_b16 v[178:179], v14 offset:1152
	ds_read_b64_tr_b16 v[192:193], v15 offset:0
	ds_read_b64_tr_b16 v[194:195], v15 offset:192
	ds_read_b128 v[164:167], v13 offset:64
	s_waitcnt lgkmcnt(5)
	v_mfma_f32_16x16x32_f16 v[136:139], v[56:59], v[160:163], 0
	ds_read_b64_tr_b16 v[180:181], v14 offset:9216
	ds_read_b64_tr_b16 v[182:183], v14 offset:10368
	ds_read_b64_tr_b16 v[196:197], v15 offset:1536
	ds_read_b64_tr_b16 v[198:199], v15 offset:1728
	s_waitcnt lgkmcnt(5)
	v_mfma_f32_16x16x32_f16 v[140:143], v[176:179], v[192:195], 0
	ds_read_b128 v[168:171], v13 offset:128
	s_waitcnt lgkmcnt(5)
	v_mfma_f32_16x16x32_f16 v[136:139], v[60:63], v[164:167], v[136:139]
	ds_read_b64_tr_b16 v[184:185], v14 offset:18432
	ds_read_b64_tr_b16 v[186:187], v14 offset:19584
	ds_read_b64_tr_b16 v[200:201], v15 offset:3072
	ds_read_b64_tr_b16 v[202:203], v15 offset:3264
	s_waitcnt lgkmcnt(5)
	v_mfma_f32_16x16x32_f16 v[140:143], v[180:183], v[196:199], v[140:143]
	ds_read_b128 v[172:175], v13 offset:192
	s_waitcnt lgkmcnt(5)
	v_mfma_f32_16x16x32_f16 v[136:139], v[64:67], v[168:171], v[136:139]
	ds_read_b64_tr_b16 v[188:189], v14 offset:27648
	ds_read_b64_tr_b16 v[190:191], v14 offset:28800
	ds_read_b64_tr_b16 v[204:205], v15 offset:4608
	ds_read_b64_tr_b16 v[206:207], v15 offset:4800
	s_waitcnt lgkmcnt(5)
	v_mfma_f32_16x16x32_f16 v[140:143], v[184:187], v[200:203], v[140:143]
	s_waitcnt lgkmcnt(4)
	v_mfma_f32_16x16x32_f16 v[136:139], v[68:71], v[172:175], v[136:139]
	s_waitcnt lgkmcnt(0)
	v_mfma_f32_16x16x32_f16 v[140:143], v[188:191], v[204:207], v[140:143]
	s_nop 7
	s_nop 1
	v_mul_f32_e32 v208, v136, v128
	v_mul_f32_e32 v209, v137, v129
	v_mul_f32_e32 v210, v138, v130
	v_mul_f32_e32 v211, v139, v131
	v_cvt_f16_f32_e32 v208, v208
	v_cvt_f16_f32_e32 v209, v209
	v_cvt_f16_f32_e32 v210, v210
	v_cvt_f16_f32_e32 v211, v211
	global_store_short v17, v208, s[28:29]
	global_store_short v17, v209, s[28:29] offset:2048
	global_store_short v18, v210, s[28:29]
	global_store_short v18, v211, s[28:29] offset:2048
	v_fma_f32 v132, s13, v132, v140
	v_fma_f32 v133, s13, v133, v141
	v_fma_f32 v134, s13, v134, v142
	v_fma_f32 v135, s13, v135, v143
	v_cvt_pk_f16_f32 v212, v132, v133
	v_cvt_pk_f16_f32 v213, v134, v135
	ds_write_b64 v16, v[212:213] offset:4352
	s_add_u32 s26, s11, 3
	s_cmp_ge_u32 s26, 0x82
	s_cbranch_scc1 .Lri_nopf_4
	s_cmp_lt_u32 s26, 2
	s_cbranch_scc0 .Lri_lat_12
	s_sub_u32 s1, 1, s26
	s_cmp_lg_u32 s8, 0
	s_cselect_b32 s1, s1, s26
	s_lshl_b32 s1, s1, 7
	s_lshl_b32 s14, s10, 8
	s_add_u32 s1, s1, s14
	s_add_u32 s1, s1, 0x8000
	s_branch .Lri_rowdone_12

; __device__ __forceinline__ void ph_ret_inter(const Params& P, char* smem) {
;     ...
;       __syncthreads();
; #pragma unroll
;       for (int k_ = 0; k_ < 4; ++k_) {
;         const int i_ = tid + k_ * NTHR, t_ = i_ / 16, c8_ = i_ % 16;
;         *(h16x8*)(Qs + t_ * LDR + c8_ * 8) = rq[k_]; *(h16x8*)(Ks + t_ * LDR + c8_ * 8) = rk[k_];
;       }
;       if (tid < 256) {
;         const int t_ = tid / 2; const float w = wk[t_];
;         h16x8 o8;
; #pragma unroll
;         for (int j = 0; j < 8; ++j) o8[j] = (h16)(w * (float)rv[j]);
;         *(h16x8*)(Vs + t_ * 24 + (tid % 2) * 8) = o8;
;       }
.Lri_w_5:
	s_waitcnt vmcnt(13)
	s_cmp_ge_u32 s11, 0x81
	s_cbranch_scc1 .Lri_nokv_5
	ds_write_b128 v10, v[36:39] offset:0
	ds_write_b128 v10, v[40:43] offset:9216
	ds_write_b128 v10, v[44:47] offset:18432
	ds_write_b128 v10, v[48:51] offset:27648
	s_cmp_gt_u32 s0, 3
	s_cbranch_scc1 .Lri_nov_6
	v_cvt_f32_f16_e32 v208, v52
	v_cvt_f32_f16_sdwa v209, v52 dst_sel:DWORD dst_unused:UNUSED_PAD src0_sel:WORD_1
	v_cvt_f32_f16_e32 v210, v53
	v_cvt_f32_f16_sdwa v211, v53 dst_sel:DWORD dst_unused:UNUSED_PAD src0_sel:WORD_1
	v_cvt_f32_f16_e32 v212, v54
	v_cvt_f32_f16_sdwa v213, v54 dst_sel:DWORD dst_unused:UNUSED_PAD src0_sel:WORD_1
	v_cvt_f32_f16_e32 v214, v55
	v_cvt_f32_f16_sdwa v215, v55 dst_sel:DWORD dst_unused:UNUSED_PAD src0_sel:WORD_1
	v_mul_f32_e32 v208, v19, v208
	v_mul_f32_e32 v209, v19, v209
	v_mul_f32_e32 v210, v19, v210
	v_mul_f32_e32 v211, v19, v211
	v_mul_f32_e32 v212, v19, v212
	v_mul_f32_e32 v213, v19, v213
	v_mul_f32_e32 v214, v19, v214
	v_mul_f32_e32 v215, v19, v215
	v_cvt_pk_f16_f32 v216, v208, v209
	v_cvt_pk_f16_f32 v217, v210, v211
	v_cvt_pk_f16_f32 v218, v212, v213
	v_cvt_pk_f16_f32 v219, v214, v215
	ds_write_b128 v11, v[216:219]

; #define MFMA16(a, b, c) emu_mfma16(a, b, c)
; #define MFMA16(a, b, c) __builtin_amdgcn_mfma_f32_16x16x32_f16(a, b, c, 0, 0, 0)
; __device__ __forceinline__ void ph_ret_inter(const Params& P, char* smem) {
;     ...
;       f32x4 accY = (f32x4){0.f, 0.f, 0.f, 0.f};
;       f32x4 accU = (f32x4){0.f, 0.f, 0.f, 0.f};
; #pragma unroll
;       for (int ks = 0; ks < 4; ++ks) {
;         const int ko = ks * 32 + (lane >> 4) * 8;
;         const h16x8 aq = *(const h16x8*)(Qs + (wave * 16 + (lane & 15)) * LDR + ko);
;         const h16x8 bs = *(const h16x8*)(Scur + (lane & 15) * LDR + ko);
;         accY = MFMA16(aq, bs, accY);
;         const h16x8 ak = frag_rows(Ks, LDR, ko, wave * 16 + (lane & 15));
;         const h16x8 bv = frag_rows(Vs, 24, ko, lane & 15);
;         accU = MFMA16(ak, bv, accU);
;       }
;       h16x4 sv;
; #pragma unroll
;       for (int i = 0; i < 4; ++i) {
;         const int j = wave * 16 + (lane >> 4) * 4 + i;
;         yint[((size_t)dir * NT + row0 + j) * RETW + h * RET_HD + dvs * 16 + (lane & 15)] = (h16)(accY[i] * dec[j]);
;         accS[i] = gC * accS[i] + accU[i];
;         sv[i] = (h16)accS[i];
;       }
;       *(h16x4*)(Snxt + (lane & 15) * LDR + wave * 16 + (lane >> 4) * 4) = sv;
;     }
.Lri_rowdone_13:
	s_mul_i32 s14, s8, 0x8200
	s_add_u32 s14, s14, s1
	s_lshl_b32 s15, s14, 11
	s_lshr_b32 s14, s14, 21
	s_add_u32 s28, s16, s15
	s_addc_u32 s29, s17, s14
	ds_read_b128 v[160:163], v13 offset:4352
	ds_read_b64_tr_b16 v[176:177], v12 offset:0
	ds_read_b64_tr_b16 v[178:179], v12 offset:1152
	ds_read_b64_tr_b16 v[192:193], v15 offset:6144
	ds_read_b64_tr_b16 v[194:195], v15 offset:6336
	ds_read_b128 v[164:167], v13 offset:4416
	s_waitcnt lgkmcnt(5)
	v_mfma_f32_16x16x32_f16 v[136:139], v[92:95], v[160:163], 0
	ds_read_b64_tr_b16 v[180:181], v12 offset:9216
	ds_read_b64_tr_b16 v[182:183], v12 offset:10368
	ds_read_b64_tr_b16 v[196:197], v15 offset:7680
	ds_read_b64_tr_b16 v[198:199], v15 offset:7872
	s_waitcnt lgkmcnt(5)
	v_mfma_f32_16x16x32_f16 v[140:143], v[176:179], v[192:195], 0
	ds_read_b128 v[168:171], v13 offset:4480
	s_waitcnt lgkmcnt(5)
	v_mfma_f32_16x16x32_f16 v[136:139], v[96:99], v[164:167], v[136:139]
	ds_read_b64_tr_b16 v[184:185], v12 offset:18432
	ds_read_b64_tr_b16 v[186:187], v12 offset:19584
	ds_read_b64_tr_b16 v[200:201], v15 offset:9216
	ds_read_b64_tr_b16 v[202:203], v15 offset:9408
	s_waitcnt lgkmcnt(5)
	v_mfma_f32_16x16x32_f16 v[140:143], v[180:183], v[196:199], v[140:143]
	ds_read_b128 v[172:175], v13 offset:4544
	s_waitcnt lgkmcnt(5)
	v_mfma_f32_16x16x32_f16 v[136:139], v[100:103], v[168:171], v[136:139]
	ds_read_b64_tr_b16 v[188:189], v12 offset:27648
	ds_read_b64_tr_b16 v[190:191], v12 offset:28800
	ds_read_b64_tr_b16 v[204:205], v15 offset:10752
	ds_read_b64_tr_b16 v[206:207], v15 offset:10944
	s_waitcnt lgkmcnt(5)
	v_mfma_f32_16x16x32_f16 v[140:143], v[184:187], v[200:203], v[140:143]
	s_waitcnt lgkmcnt(4)
	v_mfma_f32_16x16x32_f16 v[136:139], v[104:107], v[172:175], v[136:139]
	s_waitcnt lgkmcnt(0)
	v_mfma_f32_16x16x32_f16 v[140:143], v[188:191], v[204:207], v[140:143]
	s_nop 7
	s_nop 1
	v_mul_f32_e32 v208, v136, v128
	v_mul_f32_e32 v209, v137, v129
	v_mul_f32_e32 v210, v138, v130
	v_mul_f32_e32 v211, v139, v131
	v_cvt_f16_f32_e32 v208, v208
	v_cvt_f16_f32_e32 v209, v209
	v_cvt_f16_f32_e32 v210, v210
	v_cvt_f16_f32_e32 v211, v211
	global_store_short v17, v208, s[28:29]
	global_store_short v17, v209, s[28:29] offset:2048
	global_store_short v18, v210, s[28:29]
	global_store_short v18, v211, s[28:29] offset:2048
	v_fma_f32 v132, s13, v132, v140
	v_fma_f32 v133, s13, v133, v141
	v_fma_f32 v134, s13, v134, v142
	v_fma_f32 v135, s13, v135, v143
	v_cvt_pk_f16_f32 v212, v132, v133
	v_cvt_pk_f16_f32 v213, v134, v135
	ds_write_b64 v16, v[212:213] offset:0
	s_add_u32 s26, s11, 3
	s_cmp_ge_u32 s26, 0x82
	s_cbranch_scc1 .Lri_nopf_5
	s_cmp_lt_u32 s26, 2
	s_cbranch_scc0 .Lri_lat_14
	s_sub_u32 s1, 1, s26
	s_cmp_lg_u32 s8, 0
	s_cselect_b32 s1, s1, s26
	s_lshl_b32 s1, s1, 7
	s_lshl_b32 s14, s10, 8
	s_add_u32 s1, s1, s14
	s_add_u32 s1, s1, 0x8000
	s_branch .Lri_rowdone_14

; __device__ __forceinline__ void ph_ret_inter(const Params& P, char* smem) {
;     ...
;   for (int u = blockIdx.x; u < NU; u += gridDim.x) {
;     const int dvs = u % 8, dir = (u / 8) % 2, h = (u / 16) % RET_HEADS, b = u / (16 * RET_HEADS);
;     const float lg = ret_lg(h, dir);
;     const float gC = expf(lg * (float)RET_C);
;     __syncthreads();
;     ...
;     for (int o = 0; o < RET_NCH; ++o) {
;       const int row0 = ret_chunk_row(b, chunk_of(o));
;       const h16* Scur = St + (o & 1) * 16 * LDR;
;       h16* Snxt = St + ((o + 1) & 1) * 16 * LDR;
;       __syncthreads();
.Lri_nopf_5:
	s_add_u32 s11, s11, 1
	s_waitcnt lgkmcnt(0)
	s_barrier
	s_branch .Lri_chunk_loop
.Lri_unit_done:
	s_waitcnt vmcnt(0) lgkmcnt(0)
	s_barrier
	s_add_u32 s6, s6, s84
	s_cmp_lt_u32 s6, 0x100
	s_cbranch_scc1 .Lri_unit

; #define RW_LOAD(slot, step) do { const size_t ro_ = (size_t)row_of(step) * RWW; \
;       s_ok[slot] = *(const h16x8*)((p_rec + ro_ * 3) + urec); s_b[slot] = *(const h16x4*)((p_rec + ro_ * 3) + urec + 8); \
;       s_kr[slot] = *(const h16x8*)((p_sh + ro_ * 2) + ush); s_v[slot] = (p_v + ro_)[uvoff]; } while (0)
; template <int VAR>
; __device__ __forceinline__ void ph_rw_scan(const Params& P) {
;     ...
;   for (int wu = blockIdx.x * 4 + wave; wave < 4 && wu < NWU; wu += gridDim.x * 4) {
;     const int rg = wu % 16, hh = (wu / 16) % RW_H, b = (wu / (16 * RW_H)) % BATCH, dir = wu / (16 * RW_H * BATCH);
;     const int vrow = rg * 4 + rl;
;     ...
;     const unsigned g_ = (unsigned)(hh * 16 + q);
;     const unsigned uvoff = (unsigned)(hh * 64 + vrow), urec = g_ * 12u, ush = g_ * 8u;
;     h16x8 s_ok[RW_U], s_kr[RW_U]; h16x4 s_b[RW_U]; h16 s_v[RW_U];
;     auto row_of = [&](int step) -> int {
;       if (step < CTX_LEN) return NL + b * CTX_LEN + (dir == 0 ? step : CTX_LEN - 1 - step);
;       const int s = step - CTX_LEN; return b * SEQ + (dir == 0 ? s : SEQ - 1 - s);
;     };
;     ...
; #pragma unroll
;     for (int uu = 0; uu < RW_U; ++uu) RW_LOAD(uu, uu);
.Lscan_unit:
	s_lshr_b32 s31, s0, 2
	s_and_b32 s26, s31, 7
	s_lshr_b32 s31, s31, 3
	s_and_b32 s27, s31, 3
	s_lshr_b32 s31, s31, 2
	s_lshl_b32 s26, s26, 3
	s_add_u32 s31, s31, s26
	s_lshl_b32 s26, s27, 2
	s_add_u32 s26, s26, s1
	s_and_b32 s27, s31, 15
	s_bfe_u32 s28, s31, 0x10004
	s_lshr_b32 s29, s31, 5
	s_lshl_b32 s30, s27, 4
	v_add_u32_e32 v4, s30, v2
	v_mul_u32_u24_e32 v5, 24, v4
	v_lshlrev_b32_e32 v6, 4, v4
	s_lshl_b32 s30, s27, 6
	s_lshl_b32 s31, s26, 2
	s_add_u32 s30, s30, s31
	v_add_u32_e32 v7, s30, v3
	v_lshlrev_b32_e32 v7, 1, v7
	s_cmp_lg_u32 s29, 0
	s_cbranch_scc1 .Lscan_dir1
	s_lshl_b32 s30, s1, 2
	v_add_u32_e32 v39, s30, v3
	v_mul_u32_u24_e32 v48, 0x1800, v39
	v_add_u32_e32 v48, v48, v5
	v_lshlrev_b32_e32 v49, 12, v39
	v_add_u32_e32 v49, v49, v6
	v_lshlrev_b32_e32 v38, 11, v2
	v_add_u32_e32 v38, v38, v7
	s_lshl_b32 s30, s28, 8
	s_add_u32 s30, s30, 0x8000
	s_lshl_b32 s31, s28, 14
	s_mul_i32 s3, s30, 0x1800
	s_add_u32 s6, s4, s3
	s_addc_u32 s7, s5, 0
	s_add_u32 s6, s6, 0x23614000
	s_addc_u32 s7, s7, 0
	s_mul_i32 s3, s30, 0x1000
	s_add_u32 s8, s4, s3
	s_addc_u32 s9, s5, 0
	s_add_u32 s8, s8, 0xbe4c000
	s_addc_u32 s9, s9, 0
	s_mul_i32 s3, s30, 0x800
	s_add_u32 s10, s4, s3
	s_addc_u32 s11, s5, 0
	s_add_u32 s10, s10, 0x3bc14000
	s_addc_u32 s11, s11, 0
	s_mul_i32 s3, s31, 0x1800
	s_add_u32 s14, s4, s3
	s_addc_u32 s15, s5, 0
	s_add_u32 s14, s14, 0x23614000
	s_addc_u32 s15, s15, 0
	s_mul_i32 s3, s31, 0x1000
	s_add_u32 s16, s4, s3
	s_addc_u32 s17, s5, 0
	s_add_u32 s16, s16, 0xbe4c000
	s_addc_u32 s17, s17, 0
	s_mul_i32 s3, s31, 0x800
	s_add_u32 s18, s4, s3
	s_addc_u32 s19, s5, 0
	s_add_u32 s18, s18, 0x3bc14000
	s_addc_u32 s19, s19, 0
	s_mul_i32 s3, s31, 0x800
	s_add_u32 s12, s4, s3
	s_addc_u32 s13, s5, 0
	s_add_u32 s12, s12, 0x160cc000
	s_addc_u32 s13, s13, 0
	v_mov_b32_e32 v10, 0
	v_mov_b32_e32 v11, 0
	v_mov_b32_e32 v12, 0
	v_mov_b32_e32 v13, 0
	s_mov_b32 s29, 0
	global_load_ushort v36, v38, s[10:11]
	s_mov_b32 s26, 0
	s_mov_b32 s27, 10240
	s_mov_b32 s28, 0
	v_add_u32_e32 v40, s26, v8
	v_add_u32_e32 v41, s26, v9
	v_add_u32_e32 v42, s27, v8
	v_add_u32_e32 v43, s27, v9
	v_add_u32_e32 v44, s28, v46
	v_add_u32_e32 v45, s28, v47
	global_load_dwordx4 v[50:53], v48, s[6:7]
	global_load_dwordx2 v[54:55], v48, s[6:7] offset:16
	global_load_dwordx4 v[56:59], v49, s[8:9]
	s_add_u32 s29, s29, 1
	s_cmp_eq_u32 s29, 16
	s_cbranch_scc1 .Lscan_stsw_p0_d0
	s_add_u32 s6, s6, 0x18000
	s_addc_u32 s7, s7, 0
	s_add_u32 s8, s8, 0x10000
	s_addc_u32 s9, s9, 0
	s_branch .Lscan_stdone_p0_d0
